# out-proj..final-norm chain: grid barriers replaced by 4-workgroup token-tile group sync (same XCD), ffn/final rmsnorm rows remapped to the group's own token tile
# speedup vs baseline: 1.0134x; 1.0106x over previous
; __global__ void __launch_bounds__(NTHR) fwd_megakernel(const Params P) {
;     ...
;   if (threadIdx.x == 0) {
;     bool even = (gridDim.x & 7u) == 0u;
;     for (int j = 0; j < 8; ++j)
;       even = even && (__hip_atomic_load((unsigned*)(P.ws + OFF_CTL + 8192) + j, __ATOMIC_RELAXED, __HIP_MEMORY_SCOPE_AGENT) == gridDim.x / 8u);
;     s_vb[0] = even ? (s_vb[1] + 8 * s_vb[2]) : (int)blockIdx.x;
;   }
.LBB0_115:
	v_mov_b32_e32 v2, 0
	ds_read_b64 v[0:1], v2 offset:24
	s_waitcnt lgkmcnt(0)
	v_lshlrev_b32_e32 v0, 3, v0
	v_add_u32_e32 v0, v0, v1
	v_mov_b32_e32 v1, s41
	v_cndmask_b32_e64 v0, v1, v0, s[2:3]
	ds_write_b32 v2, v0 offset:16
	v_cndmask_b32_e64 v1, 0, 1, s[2:3]
	ds_write_b32 v2, v1 offset:28

; #define LAS __attribute__((address_space(3)))
; __device__ __forceinline__ unsigned xb_ld(unsigned* p) { return __hip_atomic_load(p, __ATOMIC_RELAXED, __HIP_MEMORY_SCOPE_AGENT); }
; __device__ __forceinline__ unsigned xb_add(unsigned* p, unsigned v) { return __hip_atomic_fetch_add(p, v, __ATOMIC_RELAXED, __HIP_MEMORY_SCOPE_AGENT); }
; __device__ __forceinline__ unsigned xb_xcc_id() { return (unsigned)__builtin_amdgcn_s_getreg((3 << 11) | 20) & 0xFu; }
; #define XB_SPIN(cond, bar) do { unsigned _sp = 0; while (cond) { __builtin_amdgcn_s_sleep(1); \
;     if ((++_sp & 255u) == 0u) { if (xb_ld(&(bar)[XB_TMO])) break; if (_sp > XB_SPIN_CAP) { atomicAdd(&(bar)[XB_TMO], 1u); break; } } } } while (0)
; __device__ __forceinline__ void xcd_barrier(const Params& P, volatile LAS unsigned* st, const int wvi) {
;   XcdBarrier b; b.bar = (unsigned*)(wsp_plain(P) + OFF_CTL + 65536); b.x = xb_xcc_id(); b.st = st;
;   asm volatile("s_waitcnt vmcnt(0)" ::: "memory");
;   __syncthreads();
;   if (tidx(wvi) == 0) {
;     unsigned* bar = b.bar;
;     __builtin_amdgcn_s_waitcnt(0);
;     unsigned nloc = b.st[0], nx = b.st[1];
;     if (nloc == 0u) { xcd_barrier_complete(bar, b.x, nloc, nx); b.st[0] = nloc; b.st[1] = nx; }
;     const unsigned old = xb_add(&bar[XB_XSUB(b.x)], 1u);
;     const unsigned gen = old / nloc;
;     if (old + 1u == (gen + 1u) * nloc) {
;       __builtin_amdgcn_fence(__ATOMIC_RELEASE, "agent");
;       asm volatile("s_waitcnt vmcnt(0)" ::: "memory");
;       const unsigned og = xb_add(&bar[XB_TOP], 1u);
;       const unsigned tg = og / nx;
;       if (og + 1u == (tg + 1u) * nx) xb_add(&bar[XB_TOPGEN], 1u);
;       else XB_SPIN(xb_ld(&bar[XB_TOPGEN]) == tg, bar);
;       __builtin_amdgcn_fence(__ATOMIC_ACQUIRE, "agent");
;       xb_add(&bar[XB_XGEN(b.x)], 1u);
;       asm volatile("s_waitcnt vmcnt(0)" ::: "memory");
;     } else {
;       XB_SPIN(xb_ld(&bar[XB_XGEN(b.x)]) == gen, bar);
;       __builtin_amdgcn_fence(__ATOMIC_ACQUIRE, "agent");
;       asm volatile("s_waitcnt vmcnt(0)" ::: "memory");
;     }
;   }
;   __syncthreads();
; }
.LBB0_898:
	s_getreg_b32 s2, hwreg(HW_REG_XCC_ID, 0, 4)
	s_waitcnt vmcnt(0)
	v_readlane_b32 s0, v246, 2
	s_waitcnt lgkmcnt(0)
	s_barrier
	v_mbcnt_lo_u32_b32 v0, -1, 0
	v_mbcnt_hi_u32_b32 v0, -1, v0
	s_nop 0
	v_cmp_eq_u32_e32 vcc, s0, v0
	s_and_saveexec_b64 s[0:1], vcc
	s_cbranch_execz .LBB0_950
	v_readlane_b32 s4, v244, 20
	s_nop 3
	s_cmpk_lg_i32 s4, 0x100
	s_cbranch_scc1 .Lgrp8_old
	ds_read_b32 v1, v145 offset:28
	ds_read_b32 v0, v145 offset:16
	s_waitcnt vmcnt(0) lgkmcnt(0)
	v_readfirstlane_b32 s4, v1
	s_nop 3
	s_cmp_lg_u32 s4, 1
	s_cbranch_scc1 .Lgrp8_old
	v_readfirstlane_b32 s2, v0
	s_nop 3
	s_and_b32 s2, s2, 63
	s_lshl_b32 s2, s2, 6
	s_add_u32 s4, s50, 0x3df04000
	s_addc_u32 s5, s51, 0
	s_add_u32 s4, s4, s2
	s_addc_u32 s5, s5, 0
	v_mov_b32_e32 v1, 1
	s_nop 1
	global_atomic_add v0, v145, v1, s[4:5] sc0
	s_waitcnt vmcnt(0)
	v_readfirstlane_b32 s6, v0
	s_nop 3
	s_and_b32 s6, s6, -4
	s_add_i32 s6, s6, 4
	s_mov_b32 s2, 0
.Lgrp8_spin:
	global_load_dword v0, v145, s[4:5] sc1
	s_waitcnt vmcnt(0)
	v_readfirstlane_b32 s7, v0
	s_nop 3
	s_sub_i32 s7, s7, s6
	s_cmp_ge_i32 s7, 0
	s_cbranch_scc1 .Lgrp8_done
	s_add_i32 s2, s2, 1
	s_cmp_gt_u32 s2, 0x4000
	s_cbranch_scc1 .Lgrp8_done
	s_sleep 1
	s_branch .Lgrp8_spin
.Lgrp8_done:
	buffer_inv sc1
	s_waitcnt vmcnt(0)
	s_branch .LBB0_950
.Lgrp8_old:
	s_waitcnt vmcnt(0) expcnt(0) lgkmcnt(0)
	ds_read_b32 v2, v145
	ds_read_b32 v0, v145 offset:4
	s_and_b32 s8, s2, 15
	s_waitcnt lgkmcnt(1)
	v_cmp_ne_u32_e32 vcc, 0, v2
	s_cbranch_vccnz .LBB0_914
	s_mov_b32 s9, 1
	s_branch .LBB0_902

; __device__ __forceinline__ float bflo(unsigned u) { return __uint_as_float(u << 16); }
; __device__ __forceinline__ float bfhi(unsigned u) { return __uint_as_float(u & 0xffff0000u); }
; template <bool OUTF32>
; __device__ __forceinline__ void rmsnorm_rows_bf16(const u16* src, const float* w, u16* dst, float* dstf, const int wvi) {
;   const int tid = tidx(wvi);
;   const int lane = tid & 63, wv = __builtin_amdgcn_readfirstlane(tid >> 6);
;   float4 gw0[4], gw1[4];
; #pragma unroll
;   for (int i = 0; i < 4; ++i) { gw0[i] = *(const float4*)(w + i * 512 + lane * 8); gw1[i] = *(const float4*)(w + i * 512 + lane * 8 + 4); }
;   for (int row = blockIdx.x * 8 + wv; row < PT; row += gridDim.x * 8) {
;     uint4 r[4];
;     float ss = 0.f;
; #pragma unroll
;     for (int i = 0; i < 4; ++i) {
;       r[i] = *(const uint4*)(src + (size_t)row * DM + i * 512 + lane * 8);
;       const float f0 = bflo(r[i].x), f1 = bfhi(r[i].x), f2 = bflo(r[i].y), f3 = bfhi(r[i].y);
;       const float f4 = bflo(r[i].z), f5 = bfhi(r[i].z), f6 = bflo(r[i].w), f7 = bfhi(r[i].w);
;       ss += f0 * f0 + f1 * f1 + f2 * f2 + f3 * f3 + f4 * f4 + f5 * f5 + f6 * f6 + f7 * f7;
;     }
;     ss = wave_sum(ss, lane);
.LBB0_950:
	s_or_b64 exec, exec, s[0:1]
	s_waitcnt lgkmcnt(0)
	s_barrier
	v_mbcnt_lo_u32_b32 v0, -1, 0
	v_mbcnt_hi_u32_b32 v0, -1, v0
	v_readlane_b32 s1, v246, 6
	v_add_u32_e32 v1, s48, v0
	s_nop 0
	v_readfirstlane_b32 s0, v1
	s_ashr_i32 s0, s0, 6
	v_readlane_b32 s2, v244, 20
	s_nop 3
	s_cmpk_lg_i32 s2, 0x100
	s_cbranch_scc1 .Lrms1_old
	ds_read_b32 v2, v145 offset:28
	ds_read_b32 v1, v145 offset:16
	s_waitcnt lgkmcnt(0)
	v_readfirstlane_b32 s2, v2
	s_nop 3
	s_cmp_lg_u32 s2, 1
	s_cbranch_scc1 .Lrms1_old
	v_readfirstlane_b32 s1, v1
	s_nop 3
	s_and_b32 s2, s1, 63
	s_lshl_b32 s2, s2, 8
	s_lshr_b32 s1, s1, 6
	s_lshl_b32 s1, s1, 6
	s_add_i32 s1, s1, s2
	s_add_i32 s100, s1, 64
	s_movk_i32 s101, 8
	s_branch .Lrms1_join
.Lrms1_old:
	s_movk_i32 s100, 0x4000
	s_mov_b32 s101, s31
.Lrms1_join:
	s_add_i32 s0, s0, s1
	s_cmpk_gt_i32 s0, 0x3fff
	s_cbranch_scc1 .LBB0_953
	v_and_b32_e32 v34, 63, v0
	v_readlane_b32 s2, v244, 42
	v_lshlrev_b32_e32 v144, 5, v34
	v_readlane_b32 s3, v244, 43
	s_nop 4
	global_load_dwordx4 v[0:3], v144, s[2:3] offset:16
	global_load_dwordx4 v[4:7], v144, s[2:3]
	global_load_dwordx4 v[8:11], v144, s[2:3] offset:2064
	global_load_dwordx4 v[12:15], v144, s[2:3] offset:2048
	v_lshl_add_u64 v[24:25], s[2:3], 0, v[144:145]
	s_mov_b64 s[2:3], 0x1000
	s_movk_i32 s1, 0x1000
	v_lshl_add_u64 v[20:21], v[24:25], 0, s[2:3]
	v_add_co_u32_e32 v26, vcc, s1, v24
	s_mov_b64 s[2:3], 0x1800
	s_nop 0
	v_addc_co_u32_e32 v27, vcc, 0, v25, vcc
	v_lshl_add_u64 v[28:29], v[24:25], 0, s[2:3]
	global_load_dwordx4 v[16:19], v[26:27], off
	s_nop 0
	global_load_dwordx4 v[20:23], v[20:21], off offset:16
	s_nop 0
	global_load_dwordx4 v[24:27], v[26:27], off offset:2048
	s_nop 0
	global_load_dwordx4 v[28:31], v[28:29], off offset:16
	v_readlane_b32 s2, v245, 25
	v_lshlrev_b32_e32 v144, 4, v34
	v_readlane_b32 s3, v245, 26
	v_lshlrev_b32_e32 v34, 2, v34
	s_waitcnt vmcnt(11)
	v_xor_b32_e32 v70, 0x80, v34
	v_lshl_add_u64 v[32:33], s[2:3], 0, v[144:145]
	v_xor_b32_e32 v71, 64, v34
	v_xor_b32_e32 v72, 32, v34
	v_xor_b32_e32 v73, 16, v34
	v_xor_b32_e32 v74, 8, v34
	v_xor_b32_e32 v75, 4, v34
	v_lshl_add_u64 v[34:35], s[76:77], 0, v[144:145]
.LBB0_952:
	s_ashr_i32 s1, s0, 31
	s_lshl_b64 s[2:3], s[0:1], 12
	v_lshl_add_u64 v[54:55], v[32:33], 0, s[2:3]
	global_load_dwordx4 v[36:39], v[54:55], off
	global_load_dwordx4 v[58:61], v[54:55], off offset:2048
	s_add_i32 s0, s0, s101
	s_cmp_lt_i32 s0, s100
	global_load_dwordx4 v[76:79], v[54:55], off offset:3072
	s_waitcnt vmcnt(2)
	v_lshlrev_b32_e32 v68, 16, v36
	v_and_b32_e32 v69, 0xffff0000, v36
	v_lshlrev_b32_e32 v64, 16, v37
	v_and_b32_e32 v65, 0xffff0000, v37
	v_lshlrev_b32_e32 v52, 16, v38
	v_and_b32_e32 v53, 0xffff0000, v38
	v_lshlrev_b32_e32 v46, 16, v39
	v_and_b32_e32 v47, 0xffff0000, v39
	global_load_dwordx4 v[36:39], v[54:55], off offset:1024
	v_mov_b32_e32 v90, v69
	s_waitcnt vmcnt(2)
	v_and_b32_e32 v49, 0xffff0000, v58
	v_mov_b32_e32 v88, v68
	v_lshlrev_b32_e32 v48, 16, v58
	v_mov_b32_e32 v84, v64
	v_mov_b32_e32 v92, v49
	v_lshlrev_b32_e32 v42, 16, v59
	v_mov_b32_e32 v86, v65
	v_and_b32_e32 v43, 0xffff0000, v59
	v_mov_b32_e32 v80, v52
	v_mov_b32_e32 v82, v53
	v_lshl_add_u64 v[54:55], v[34:35], 0, s[2:3]
	s_waitcnt vmcnt(1)
	v_and_b32_e32 v67, 0xffff0000, v76
	v_lshlrev_b32_e32 v66, 16, v76
	v_lshlrev_b32_e32 v62, 16, v77
	v_and_b32_e32 v63, 0xffff0000, v77
	v_mov_b32_e32 v76, v46
	v_lshlrev_b32_e32 v58, 16, v79
	v_and_b32_e32 v59, 0xffff0000, v79
	v_mov_b32_e32 v93, v67
	v_pk_mul_f32 v[92:93], v[92:93], v[92:93]
	s_waitcnt vmcnt(0)
	v_and_b32_e32 v57, 0xffff0000, v36
	v_lshlrev_b32_e32 v56, 16, v36
	v_mov_b32_e32 v91, v57
	v_lshlrev_b32_e32 v50, 16, v37
	v_mov_b32_e32 v89, v56
	v_pk_mul_f32 v[90:91], v[90:91], v[90:91]
	v_and_b32_e32 v51, 0xffff0000, v37
	v_mov_b32_e32 v85, v50
	v_pk_fma_f32 v[88:89], v[88:89], v[88:89], v[90:91]
	v_lshlrev_b32_e32 v44, 16, v38
	v_mov_b32_e32 v87, v51
	v_pk_fma_f32 v[84:85], v[84:85], v[84:85], v[88:89]
	v_mov_b32_e32 v90, v48
	v_mov_b32_e32 v91, v66
	v_and_b32_e32 v45, 0xffff0000, v38
	v_mov_b32_e32 v81, v44
	v_pk_fma_f32 v[84:85], v[86:87], v[86:87], v[84:85]
	v_mov_b32_e32 v86, v42
	v_mov_b32_e32 v87, v62
	v_pk_fma_f32 v[90:91], v[90:91], v[90:91], v[92:93]
	v_lshlrev_b32_e32 v40, 16, v39
	v_and_b32_e32 v41, 0xffff0000, v39
	v_lshlrev_b32_e32 v38, 16, v60
	v_and_b32_e32 v39, 0xffff0000, v60
	v_lshlrev_b32_e32 v60, 16, v78
	v_mov_b32_e32 v83, v45
	v_pk_fma_f32 v[80:81], v[80:81], v[80:81], v[84:85]
	v_mov_b32_e32 v88, v43
	v_mov_b32_e32 v89, v63
	v_pk_fma_f32 v[86:87], v[86:87], v[86:87], v[90:91]
	v_lshlrev_b32_e32 v36, 16, v61
	v_and_b32_e32 v37, 0xffff0000, v61
	v_and_b32_e32 v61, 0xffff0000, v78
	v_mov_b32_e32 v77, v40
	v_pk_fma_f32 v[80:81], v[82:83], v[82:83], v[80:81]
	v_mov_b32_e32 v82, v38
	v_mov_b32_e32 v83, v60
	v_pk_fma_f32 v[86:87], v[88:89], v[88:89], v[86:87]
	v_mov_b32_e32 v78, v47
	v_mov_b32_e32 v79, v41
	v_pk_fma_f32 v[76:77], v[76:77], v[76:77], v[80:81]
	v_mov_b32_e32 v84, v39
	v_mov_b32_e32 v85, v61
	v_pk_fma_f32 v[82:83], v[82:83], v[82:83], v[86:87]
	v_pk_fma_f32 v[76:77], v[78:79], v[78:79], v[76:77]
	v_mov_b32_e32 v78, v36
	v_mov_b32_e32 v79, v58
	v_pk_fma_f32 v[82:83], v[84:85], v[84:85], v[82:83]
	v_mov_b32_e32 v80, v37
	v_mov_b32_e32 v81, v59
	v_pk_fma_f32 v[78:79], v[78:79], v[78:79], v[82:83]
	v_add_f32_e32 v76, v76, v77
	v_pk_fma_f32 v[78:79], v[80:81], v[80:81], v[78:79]
	s_nop 0
	v_add_f32_e32 v76, v76, v78
	v_add_f32_e32 v76, v76, v79
	ds_bpermute_b32 v77, v70, v76
	s_waitcnt lgkmcnt(0)
; __device__ __forceinline__ float bflo(unsigned u) { return __uint_as_float(u << 16); }
; __device__ __forceinline__ float bfhi(unsigned u) { return __uint_as_float(u & 0xffff0000u); }
; #define LAS __attribute__((address_space(3)))
; __device__ __forceinline__ unsigned xb_xcc_id() { return (unsigned)__builtin_amdgcn_s_getreg((3 << 11) | 20) & 0xFu; }
; __device__ __forceinline__ void xcd_barrier(const Params& P, volatile LAS unsigned* st, const int wvi) {
;   XcdBarrier b; b.bar = (unsigned*)(wsp_plain(P) + OFF_CTL + 65536); b.x = xb_xcc_id(); b.st = st;
;   asm volatile("s_waitcnt vmcnt(0)" ::: "memory");
;   __syncthreads();
;   if (tidx(wvi) == 0) {
;     unsigned* bar = b.bar;
;     __builtin_amdgcn_s_waitcnt(0);
;     unsigned nloc = b.st[0], nx = b.st[1];
;     if (nloc == 0u) { xcd_barrier_complete(bar, b.x, nloc, nx); b.st[0] = nloc; b.st[1] = nx; }
; template <bool OUTF32>
; __device__ __forceinline__ void rmsnorm_rows_bf16(const u16* src, const float* w, u16* dst, float* dstf, const int wvi) {
;     ...
;     ss = wave_sum(ss, lane);
;     const float rstd = rsqrtf(ss * (1.f / DM) + EPS);
; #pragma unroll
;     for (int i = 0; i < 4; ++i) {
;       const int c = i * 512 + lane * 8;
;       const float4 g0 = gw0[i], g1 = gw1[i];
;       if (OUTF32) {
;         float* po = dstf + (size_t)row * DM + c;
;         *(float4*)po = make_float4(bflo(r[i].x) * rstd * g0.x, bfhi(r[i].x) * rstd * g0.y, bflo(r[i].y) * rstd * g0.z, bfhi(r[i].y) * rstd * g0.w);
;         *(float4*)(po + 4) = make_float4(bflo(r[i].z) * rstd * g1.x, bfhi(r[i].z) * rstd * g1.y, bflo(r[i].w) * rstd * g1.z, bfhi(r[i].w) * rstd * g1.w);
;       } else {
;       uint4 o;
;       o.x = pk2(bflo(r[i].x) * rstd * g0.x, bfhi(r[i].x) * rstd * g0.y);
;       o.y = pk2(bflo(r[i].y) * rstd * g0.z, bfhi(r[i].y) * rstd * g0.w);
;       o.z = pk2(bflo(r[i].z) * rstd * g1.x, bfhi(r[i].z) * rstd * g1.y);
;       o.w = pk2(bflo(r[i].w) * rstd * g1.z, bfhi(r[i].w) * rstd * g1.w);
;       *(uint4*)(dst + (size_t)row * DM + c) = o;
	v_add_f32_e32 v76, v76, v77
	ds_bpermute_b32 v77, v71, v76
	s_waitcnt lgkmcnt(0)
	v_add_f32_e32 v76, v76, v77
	ds_bpermute_b32 v77, v72, v76
	s_waitcnt lgkmcnt(0)
	v_add_f32_e32 v76, v76, v77
	ds_bpermute_b32 v77, v73, v76
	s_waitcnt lgkmcnt(0)
	v_add_f32_e32 v76, v76, v77
	ds_bpermute_b32 v77, v74, v76
	s_waitcnt lgkmcnt(0)
	v_add_f32_e32 v76, v76, v77
	ds_bpermute_b32 v77, v75, v76
	s_waitcnt lgkmcnt(0)
	v_add_f32_e32 v76, v76, v77
	v_fmamk_f32 v76, v76, 0x3a000000, v165
	v_cmp_gt_f32_e32 vcc, s88, v76
	v_mul_f32_e32 v77, 0x4b800000, v76
	s_nop 0
	v_cndmask_b32_e32 v76, v76, v77, vcc
	v_rsq_f32_e32 v76, v76
	s_nop 0
	v_mul_f32_e32 v77, 0x45800000, v76
	v_cndmask_b32_e32 v80, v76, v77, vcc
	v_pk_mul_f32 v[68:69], v[80:81], v[68:69] op_sel_hi:[0,1]
	v_pk_mul_f32 v[64:65], v[80:81], v[64:65] op_sel_hi:[0,1]
	v_pk_mul_f32 v[52:53], v[80:81], v[52:53] op_sel_hi:[0,1]
	v_pk_mul_f32 v[46:47], v[80:81], v[46:47] op_sel_hi:[0,1]
	v_pk_mul_f32 v[68:69], v[4:5], v[68:69]
	v_pk_mul_f32 v[64:65], v[6:7], v[64:65]
	v_pk_mul_f32 v[52:53], v[0:1], v[52:53]
	v_pk_mul_f32 v[46:47], v[2:3], v[46:47]
	v_pk_mul_f32 v[40:41], v[80:81], v[40:41] op_sel_hi:[0,1]
	v_cvt_pk_bf16_f32 v76, v68, v69
	v_cvt_pk_bf16_f32 v77, v64, v65
	v_cvt_pk_bf16_f32 v78, v52, v53
	v_cvt_pk_bf16_f32 v79, v46, v47
	v_pk_mul_f32 v[40:41], v[10:11], v[40:41]
	global_store_dwordx4 v[54:55], v[76:79], off
	v_pk_mul_f32 v[42:43], v[80:81], v[42:43] op_sel_hi:[0,1]
	v_pk_mul_f32 v[38:39], v[80:81], v[38:39] op_sel_hi:[0,1]
	v_cvt_pk_bf16_f32 v79, v40, v41
	v_pk_mul_f32 v[40:41], v[80:81], v[48:49] op_sel_hi:[0,1]
	v_pk_mul_f32 v[36:37], v[80:81], v[36:37] op_sel_hi:[0,1]
	v_pk_mul_f32 v[40:41], v[16:17], v[40:41]
	v_pk_mul_f32 v[42:43], v[18:19], v[42:43]
	v_pk_mul_f32 v[38:39], v[20:21], v[38:39]
	v_pk_mul_f32 v[36:37], v[22:23], v[36:37]
	v_pk_mul_f32 v[46:47], v[80:81], v[56:57] op_sel_hi:[0,1]
	v_cvt_pk_bf16_f32 v40, v40, v41
	v_cvt_pk_bf16_f32 v41, v42, v43
	v_cvt_pk_bf16_f32 v42, v38, v39
	v_cvt_pk_bf16_f32 v43, v36, v37
	v_pk_mul_f32 v[36:37], v[80:81], v[66:67] op_sel_hi:[0,1]
	v_pk_mul_f32 v[38:39], v[80:81], v[62:63] op_sel_hi:[0,1]
	v_pk_mul_f32 v[46:47], v[12:13], v[46:47]
	v_pk_mul_f32 v[36:37], v[24:25], v[36:37]
	v_pk_mul_f32 v[38:39], v[26:27], v[38:39]
	v_cvt_pk_bf16_f32 v76, v46, v47
	v_pk_mul_f32 v[46:47], v[80:81], v[50:51] op_sel_hi:[0,1]
	v_pk_mul_f32 v[44:45], v[80:81], v[44:45] op_sel_hi:[0,1]
	global_store_dwordx4 v[54:55], v[40:43], off offset:2048
	v_cvt_pk_bf16_f32 v36, v36, v37
	v_cvt_pk_bf16_f32 v37, v38, v39
	v_pk_mul_f32 v[38:39], v[80:81], v[60:61] op_sel_hi:[0,1]
	v_pk_mul_f32 v[40:41], v[80:81], v[58:59] op_sel_hi:[0,1]
	v_pk_mul_f32 v[46:47], v[14:15], v[46:47]
	v_pk_mul_f32 v[44:45], v[8:9], v[44:45]
	v_pk_mul_f32 v[38:39], v[28:29], v[38:39]
	v_pk_mul_f32 v[40:41], v[30:31], v[40:41]
	v_cvt_pk_bf16_f32 v77, v46, v47
	v_cvt_pk_bf16_f32 v78, v44, v45
	v_cvt_pk_bf16_f32 v38, v38, v39
	v_cvt_pk_bf16_f32 v39, v40, v41
	global_store_dwordx4 v[54:55], v[76:79], off offset:1024
	global_store_dwordx4 v[54:55], v[36:39], off offset:3072
	s_cbranch_scc1 .LBB0_952
.LBB0_953:
	s_getreg_b32 s2, hwreg(HW_REG_XCC_ID, 0, 4)
	s_waitcnt vmcnt(0)
	v_readlane_b32 s0, v246, 2
	s_barrier
	v_mbcnt_lo_u32_b32 v0, -1, 0
	v_mbcnt_hi_u32_b32 v0, -1, v0
	s_nop 0
	v_cmp_eq_u32_e32 vcc, s0, v0
	s_and_saveexec_b64 s[0:1], vcc
	s_cbranch_execz .LBB0_1005
	v_readlane_b32 s4, v244, 20
	s_nop 3
	s_cmpk_lg_i32 s4, 0x100
	s_cbranch_scc1 .Lgrp9_old
	ds_read_b32 v1, v145 offset:28
	ds_read_b32 v0, v145 offset:16
	s_waitcnt vmcnt(0) lgkmcnt(0)
	v_readfirstlane_b32 s4, v1
	s_nop 3
	s_cmp_lg_u32 s4, 1
	s_cbranch_scc1 .Lgrp9_old
	v_readfirstlane_b32 s2, v0
	s_nop 3
	s_and_b32 s2, s2, 63
	s_lshl_b32 s2, s2, 6
	s_add_u32 s4, s50, 0x3df04000
	s_addc_u32 s5, s51, 0
	s_add_u32 s4, s4, s2
	s_addc_u32 s5, s5, 0
	v_mov_b32_e32 v1, 1
	s_nop 1
	global_atomic_add v0, v145, v1, s[4:5] sc0
	s_waitcnt vmcnt(0)
	v_readfirstlane_b32 s6, v0
	s_nop 3
	s_and_b32 s6, s6, -4
	s_add_i32 s6, s6, 4
	s_mov_b32 s2, 0

; #define LAS __attribute__((address_space(3)))
; __device__ __forceinline__ unsigned xb_add(unsigned* p, unsigned v) { return __hip_atomic_fetch_add(p, v, __ATOMIC_RELAXED, __HIP_MEMORY_SCOPE_AGENT); }
; __device__ __forceinline__ unsigned xb_xcc_id() { return (unsigned)__builtin_amdgcn_s_getreg((3 << 11) | 20) & 0xFu; }
; __device__ __forceinline__ void xcd_barrier(const Params& P, volatile LAS unsigned* st, const int wvi) {
;   XcdBarrier b; b.bar = (unsigned*)(wsp_plain(P) + OFF_CTL + 65536); b.x = xb_xcc_id(); b.st = st;
;   asm volatile("s_waitcnt vmcnt(0)" ::: "memory");
;   __syncthreads();
;   if (tidx(wvi) == 0) {
;     unsigned* bar = b.bar;
;     __builtin_amdgcn_s_waitcnt(0);
;     unsigned nloc = b.st[0], nx = b.st[1];
;     if (nloc == 0u) { xcd_barrier_complete(bar, b.x, nloc, nx); b.st[0] = nloc; b.st[1] = nx; }
;     const unsigned old = xb_add(&bar[XB_XSUB(b.x)], 1u);
;     const unsigned gen = old / nloc;
;     if (old + 1u == (gen + 1u) * nloc) {
.LBB0_1021:
	s_getreg_b32 s2, hwreg(HW_REG_XCC_ID, 0, 4)
	s_waitcnt vmcnt(0)
	v_readlane_b32 s0, v246, 2
	s_waitcnt vmcnt(0) lgkmcnt(0)
	s_barrier
	v_mbcnt_lo_u32_b32 v0, -1, 0
	v_mbcnt_hi_u32_b32 v0, -1, v0
	s_nop 0
	v_cmp_eq_u32_e32 vcc, s0, v0
	s_and_saveexec_b64 s[0:1], vcc
	s_cbranch_execz .LBB0_1073
	v_readlane_b32 s4, v244, 20
	s_nop 3
	s_cmpk_lg_i32 s4, 0x100
	s_cbranch_scc1 .Lgrp10_old
	ds_read_b32 v1, v145 offset:28
	ds_read_b32 v0, v145 offset:16
	s_waitcnt vmcnt(0) lgkmcnt(0)
	v_readfirstlane_b32 s4, v1
	s_nop 3
	s_cmp_lg_u32 s4, 1
	s_cbranch_scc1 .Lgrp10_old
	v_readfirstlane_b32 s2, v0
	s_nop 3
	s_and_b32 s2, s2, 63
	s_lshl_b32 s2, s2, 6
	s_add_u32 s4, s50, 0x3df04000
	s_addc_u32 s5, s51, 0
	s_add_u32 s4, s4, s2
	s_addc_u32 s5, s5, 0
	v_mov_b32_e32 v1, 1
	s_nop 1
	global_atomic_add v0, v145, v1, s[4:5] sc0
	s_waitcnt vmcnt(0)
	v_readfirstlane_b32 s6, v0
	s_nop 3
	s_and_b32 s6, s6, -4
	s_add_i32 s6, s6, 4
	s_mov_b32 s2, 0

; #define LAS __attribute__((address_space(3)))
; __device__ __forceinline__ unsigned xb_add(unsigned* p, unsigned v) { return __hip_atomic_fetch_add(p, v, __ATOMIC_RELAXED, __HIP_MEMORY_SCOPE_AGENT); }
; __device__ __forceinline__ unsigned xb_xcc_id() { return (unsigned)__builtin_amdgcn_s_getreg((3 << 11) | 20) & 0xFu; }
; __device__ __forceinline__ void xcd_barrier(const Params& P, volatile LAS unsigned* st, const int wvi) {
;   XcdBarrier b; b.bar = (unsigned*)(wsp_plain(P) + OFF_CTL + 65536); b.x = xb_xcc_id(); b.st = st;
;   asm volatile("s_waitcnt vmcnt(0)" ::: "memory");
;   __syncthreads();
;   if (tidx(wvi) == 0) {
;     unsigned* bar = b.bar;
;     __builtin_amdgcn_s_waitcnt(0);
;     unsigned nloc = b.st[0], nx = b.st[1];
;     if (nloc == 0u) { xcd_barrier_complete(bar, b.x, nloc, nx); b.st[0] = nloc; b.st[1] = nx; }
;     const unsigned old = xb_add(&bar[XB_XSUB(b.x)], 1u);
;     const unsigned gen = old / nloc;
;     if (old + 1u == (gen + 1u) * nloc) {
.LBB0_1088:
	s_getreg_b32 s2, hwreg(HW_REG_XCC_ID, 0, 4)
	s_waitcnt vmcnt(0)
	v_readlane_b32 s0, v246, 2
	s_waitcnt lgkmcnt(0)
	s_barrier
	v_mbcnt_lo_u32_b32 v0, -1, 0
	v_mbcnt_hi_u32_b32 v0, -1, v0
	s_nop 0
	v_cmp_eq_u32_e32 vcc, s0, v0
	s_and_saveexec_b64 s[0:1], vcc
	v_readlane_b32 s18, v243, 4
	v_readlane_b32 s20, v243, 33
	v_readlane_b32 s21, v243, 34
	v_readlane_b32 s22, v243, 35
	v_readlane_b32 s23, v243, 36
	v_readlane_b32 s24, v243, 37
	v_readlane_b32 s25, v243, 38
	v_readlane_b32 s26, v243, 39
	v_readlane_b32 s27, v243, 40
	s_cbranch_execz .LBB0_1140
	v_readlane_b32 s4, v244, 20
	s_nop 3
	s_cmpk_lg_i32 s4, 0x100
	s_cbranch_scc1 .Lgrp11_old
	ds_read_b32 v1, v145 offset:28
	ds_read_b32 v0, v145 offset:16
	s_waitcnt vmcnt(0) lgkmcnt(0)
	v_readfirstlane_b32 s4, v1
	s_nop 3
	s_cmp_lg_u32 s4, 1
	s_cbranch_scc1 .Lgrp11_old
	v_readfirstlane_b32 s2, v0
	s_nop 3
	s_and_b32 s2, s2, 63
	s_lshl_b32 s2, s2, 6
	s_add_u32 s4, s50, 0x3df04000
	s_addc_u32 s5, s51, 0
	s_add_u32 s4, s4, s2
	s_addc_u32 s5, s5, 0
	v_mov_b32_e32 v1, 1
	s_nop 1
	global_atomic_add v0, v145, v1, s[4:5] sc0
	s_waitcnt vmcnt(0)
	v_readfirstlane_b32 s6, v0
	s_nop 3
	s_and_b32 s6, s6, -4
	s_add_i32 s6, s6, 4
	s_mov_b32 s2, 0

; template <bool OUTF32>
; __device__ __forceinline__ void rmsnorm_rows_bf16(const u16* src, const float* w, u16* dst, float* dstf, const int wvi) {
;     ...
;   const int lane = tid & 63, wv = __builtin_amdgcn_readfirstlane(tid >> 6);
;   float4 gw0[4], gw1[4];
; #pragma unroll
;   for (int i = 0; i < 4; ++i) { gw0[i] = *(const float4*)(w + i * 512 + lane * 8); gw1[i] = *(const float4*)(w + i * 512 + lane * 8 + 4); }
;   for (int row = blockIdx.x * 8 + wv; row < PT; row += gridDim.x * 8) {
.Lrms2_join:
	s_add_i32 s0, s0, s1
	s_cmpk_gt_i32 s0, 0x3fff
	s_movk_i32 s1, 0x1000
	s_cbranch_scc0 .LBB0_1141
	s_getpc_b64 s[98:99]

; __device__ __forceinline__ float bflo(unsigned u) { return __uint_as_float(u << 16); }
; __device__ __forceinline__ float bfhi(unsigned u) { return __uint_as_float(u & 0xffff0000u); }
; template <bool OUTF32>
; __device__ __forceinline__ void rmsnorm_rows_bf16(const u16* src, const float* w, u16* dst, float* dstf, const int wvi) {
;     ...
;   for (int row = blockIdx.x * 8 + wv; row < PT; row += gridDim.x * 8) {
;     uint4 r[4];
;     float ss = 0.f;
; #pragma unroll
;     for (int i = 0; i < 4; ++i) {
;       r[i] = *(const uint4*)(src + (size_t)row * DM + i * 512 + lane * 8);
;       const float f0 = bflo(r[i].x), f1 = bfhi(r[i].x), f2 = bflo(r[i].y), f3 = bfhi(r[i].y);
;       const float f4 = bflo(r[i].z), f5 = bfhi(r[i].z), f6 = bflo(r[i].w), f7 = bfhi(r[i].w);
;       ss += f0 * f0 + f1 * f1 + f2 * f2 + f3 * f3 + f4 * f4 + f5 * f5 + f6 * f6 + f7 * f7;
;     }
;     ss = wave_sum(ss, lane);
;     const float rstd = rsqrtf(ss * (1.f / DM) + EPS);
; #pragma unroll
;     for (int i = 0; i < 4; ++i) {
;       const int c = i * 512 + lane * 8;
;       const float4 g0 = gw0[i], g1 = gw1[i];
;       if (OUTF32) {
;         float* po = dstf + (size_t)row * DM + c;
;         *(float4*)po = make_float4(bflo(r[i].x) * rstd * g0.x, bfhi(r[i].x) * rstd * g0.y, bflo(r[i].y) * rstd * g0.z, bfhi(r[i].y) * rstd * g0.w);
;         *(float4*)(po + 4) = make_float4(bflo(r[i].z) * rstd * g1.x, bfhi(r[i].z) * rstd * g1.y, bflo(r[i].w) * rstd * g1.z, bfhi(r[i].w) * rstd * g1.w);
.LBB0_1142:
	s_ashr_i32 s1, s0, 31
	s_lshl_b64 s[2:3], s[0:1], 12
	v_lshl_add_u64 v[42:43], v[32:33], 0, s[2:3]
	global_load_dwordx4 v[36:39], v[42:43], off
	global_load_dwordx4 v[78:81], v[42:43], off offset:3072
	s_lshl_b64 s[2:3], s[0:1], 13
	v_lshl_add_u64 v[68:69], v[34:35], 0, s[2:3]
	s_movk_i32 s1, 0x1000
	s_add_i32 s0, s0, s101
	s_cmp_lt_i32 s0, s100
	s_waitcnt vmcnt(1)
	v_lshlrev_b32_e32 v54, 16, v36
	v_and_b32_e32 v55, 0xffff0000, v36
	v_lshlrev_b32_e32 v52, 16, v37
	v_and_b32_e32 v53, 0xffff0000, v37
	v_lshlrev_b32_e32 v50, 16, v38
	v_and_b32_e32 v51, 0xffff0000, v38
	v_lshlrev_b32_e32 v48, 16, v39
	v_and_b32_e32 v49, 0xffff0000, v39
	global_load_dwordx4 v[36:39], v[42:43], off offset:1024
	s_waitcnt vmcnt(1)
	v_lshlrev_b32_e32 v46, 16, v78
	v_and_b32_e32 v47, 0xffff0000, v78
	v_lshlrev_b32_e32 v44, 16, v79
	v_and_b32_e32 v45, 0xffff0000, v79
	v_mov_b32_e32 v78, v54
	v_mov_b32_e32 v82, v53
	v_mov_b32_e32 v85, v45
	s_waitcnt vmcnt(0)
	v_lshlrev_b32_e32 v58, 16, v38
	v_and_b32_e32 v59, 0xffff0000, v38
	v_lshlrev_b32_e32 v56, 16, v39
	v_and_b32_e32 v57, 0xffff0000, v39
	global_load_dwordx4 v[38:41], v[42:43], off offset:2048
	v_and_b32_e32 v63, 0xffff0000, v36
	v_lshlrev_b32_e32 v62, 16, v36
	v_lshlrev_b32_e32 v60, 16, v37
	v_and_b32_e32 v61, 0xffff0000, v37
	v_lshlrev_b32_e32 v42, 16, v80
	v_and_b32_e32 v43, 0xffff0000, v80
	v_mov_b32_e32 v80, v55
	v_mov_b32_e32 v79, v62
	v_mov_b32_e32 v83, v61
	s_waitcnt vmcnt(0)
	v_lshlrev_b32_e32 v66, 16, v38
	v_and_b32_e32 v67, 0xffff0000, v38
	v_lshlrev_b32_e32 v64, 16, v39
	v_and_b32_e32 v65, 0xffff0000, v39
	v_lshlrev_b32_e32 v38, 16, v40
	v_and_b32_e32 v39, 0xffff0000, v40
	v_lshlrev_b32_e32 v36, 16, v41
	v_and_b32_e32 v37, 0xffff0000, v41
	v_lshlrev_b32_e32 v40, 16, v81
	v_and_b32_e32 v41, 0xffff0000, v81
	v_mov_b32_e32 v81, v63
	v_pk_mul_f32 v[80:81], v[80:81], v[80:81]
	v_mov_b32_e32 v84, v65
	v_pk_fma_f32 v[78:79], v[78:79], v[78:79], v[80:81]
	v_mov_b32_e32 v80, v52
	v_mov_b32_e32 v81, v60
	v_pk_fma_f32 v[78:79], v[80:81], v[80:81], v[78:79]
	v_mov_b32_e32 v80, v50
	v_pk_fma_f32 v[78:79], v[82:83], v[82:83], v[78:79]
	v_mov_b32_e32 v81, v58
	v_mov_b32_e32 v82, v51
	v_mov_b32_e32 v83, v59
	v_pk_fma_f32 v[78:79], v[80:81], v[80:81], v[78:79]
	v_mov_b32_e32 v80, v48
	v_pk_fma_f32 v[78:79], v[82:83], v[82:83], v[78:79]
	v_mov_b32_e32 v81, v56
	v_mov_b32_e32 v82, v49
	v_mov_b32_e32 v83, v57
	v_pk_fma_f32 v[78:79], v[80:81], v[80:81], v[78:79]
	v_mov_b32_e32 v80, v66
	v_pk_fma_f32 v[78:79], v[82:83], v[82:83], v[78:79]
	v_mov_b32_e32 v82, v67
	v_mov_b32_e32 v83, v47
	v_mov_b32_e32 v81, v46
	v_pk_mul_f32 v[82:83], v[82:83], v[82:83]
	v_add_f32_e32 v70, v78, v79
	v_pk_fma_f32 v[80:81], v[80:81], v[80:81], v[82:83]
	v_mov_b32_e32 v82, v64
	v_mov_b32_e32 v83, v44
	v_pk_fma_f32 v[80:81], v[82:83], v[82:83], v[80:81]
	v_mov_b32_e32 v82, v38
	v_pk_fma_f32 v[80:81], v[84:85], v[84:85], v[80:81]
	v_mov_b32_e32 v83, v42
	v_mov_b32_e32 v84, v39
	v_mov_b32_e32 v85, v43
	v_pk_fma_f32 v[80:81], v[82:83], v[82:83], v[80:81]
	v_mov_b32_e32 v82, v36
	v_pk_fma_f32 v[80:81], v[84:85], v[84:85], v[80:81]
	v_mov_b32_e32 v83, v40
	v_mov_b32_e32 v84, v37
	v_mov_b32_e32 v85, v41
	v_pk_fma_f32 v[80:81], v[82:83], v[82:83], v[80:81]
	s_nop 0
	v_pk_fma_f32 v[80:81], v[84:85], v[84:85], v[80:81]
	s_nop 0
	v_add_f32_e32 v70, v70, v80
	v_add_f32_e32 v70, v70, v81
	ds_bpermute_b32 v77, v71, v70
	s_waitcnt lgkmcnt(0)
	v_add_f32_e32 v70, v70, v77
	ds_bpermute_b32 v77, v72, v70
	s_waitcnt lgkmcnt(0)
	v_add_f32_e32 v70, v70, v77
	ds_bpermute_b32 v77, v73, v70
	s_waitcnt lgkmcnt(0)
	v_add_f32_e32 v70, v70, v77
	ds_bpermute_b32 v77, v74, v70
	s_waitcnt lgkmcnt(0)
	v_add_f32_e32 v70, v70, v77
	ds_bpermute_b32 v77, v75, v70
	s_waitcnt lgkmcnt(0)
	v_add_f32_e32 v70, v70, v77
	ds_bpermute_b32 v77, v76, v70
	s_waitcnt lgkmcnt(0)
	v_add_f32_e32 v70, v70, v77
	v_fmamk_f32 v70, v70, 0x3a000000, v165
	v_cmp_gt_f32_e32 vcc, s88, v70
	v_mul_f32_e32 v77, 0x4b800000, v70
	s_nop 0
	v_cndmask_b32_e32 v70, v70, v77, vcc
	v_rsq_f32_e32 v70, v70
	s_nop 0
	v_mul_f32_e32 v77, 0x45800000, v70
	v_cndmask_b32_e32 v70, v70, v77, vcc
	v_pk_mul_f32 v[52:53], v[70:71], v[52:53] op_sel_hi:[0,1]
	v_pk_mul_f32 v[50:51], v[70:71], v[50:51] op_sel_hi:[0,1]
	v_pk_mul_f32 v[48:49], v[70:71], v[48:49] op_sel_hi:[0,1]
	v_pk_mul_f32 v[80:81], v[6:7], v[52:53]
	v_pk_mul_f32 v[50:51], v[0:1], v[50:51]
	v_pk_mul_f32 v[52:53], v[2:3], v[48:49]
	global_store_dwordx4 v[68:69], v[50:53], off offset:16
	v_pk_mul_f32 v[48:49], v[70:71], v[62:63] op_sel_hi:[0,1]
	v_pk_mul_f32 v[48:49], v[12:13], v[48:49]
	v_pk_mul_f32 v[50:51], v[70:71], v[60:61] op_sel_hi:[0,1]
	v_pk_mul_f32 v[50:51], v[14:15], v[50:51]
	global_store_dwordx4 v[68:69], v[48:51], off offset:2048
	v_add_co_u32_e32 v52, vcc, s1, v68
	s_nop 0
	v_pk_mul_f32 v[48:49], v[70:71], v[58:59] op_sel_hi:[0,1]
	v_pk_mul_f32 v[50:51], v[70:71], v[56:57] op_sel_hi:[0,1]
	v_pk_mul_f32 v[48:49], v[8:9], v[48:49]
	v_pk_mul_f32 v[50:51], v[10:11], v[50:51]
	global_store_dwordx4 v[68:69], v[48:51], off offset:2064
	v_addc_co_u32_e32 v53, vcc, 0, v69, vcc
	s_nop 0
	v_pk_mul_f32 v[48:49], v[70:71], v[66:67] op_sel_hi:[0,1]
	v_pk_mul_f32 v[50:51], v[70:71], v[64:65] op_sel_hi:[0,1]
	v_pk_mul_f32 v[48:49], v[16:17], v[48:49]
	v_pk_mul_f32 v[50:51], v[18:19], v[50:51]
	v_pk_mul_f32 v[38:39], v[70:71], v[38:39] op_sel_hi:[0,1]
	v_pk_mul_f32 v[36:37], v[70:71], v[36:37] op_sel_hi:[0,1]
	global_store_dwordx4 v[52:53], v[48:51], off
	v_pk_mul_f32 v[54:55], v[70:71], v[54:55] op_sel_hi:[0,1]
	v_pk_mul_f32 v[78:79], v[4:5], v[54:55]
	v_pk_mul_f32 v[48:49], v[20:21], v[38:39]
	v_pk_mul_f32 v[50:51], v[22:23], v[36:37]
	v_pk_mul_f32 v[36:37], v[70:71], v[46:47] op_sel_hi:[0,1]
	v_pk_mul_f32 v[38:39], v[70:71], v[44:45] op_sel_hi:[0,1]
	v_pk_mul_f32 v[36:37], v[24:25], v[36:37]
	v_pk_mul_f32 v[38:39], v[26:27], v[38:39]
	global_store_dwordx4 v[52:53], v[36:39], off offset:2048
	global_store_dwordx4 v[68:69], v[78:81], off
	global_store_dwordx4 v[52:53], v[48:51], off offset:16
	v_pk_mul_f32 v[36:37], v[70:71], v[42:43] op_sel_hi:[0,1]
	v_pk_mul_f32 v[38:39], v[70:71], v[40:41] op_sel_hi:[0,1]
	v_pk_mul_f32 v[36:37], v[28:29], v[36:37]
	v_pk_mul_f32 v[38:39], v[30:31], v[38:39]
	global_store_dwordx4 v[52:53], v[36:39], off offset:2064
	s_cbranch_scc1 .LBB0_1142
	s_getpc_b64 s[98:99]

; __global__ void __launch_bounds__(NTHR) fwd_megakernel(const Params P) {
	.amdhsa_kernel _Z14fwd_megakernel6Params
		.amdhsa_group_segment_fixed_size 32
		.amdhsa_private_segment_fixed_size 0
		.amdhsa_kernarg_size 688
		.amdhsa_user_sgpr_count 2
		.amdhsa_user_sgpr_dispatch_ptr 0
		.amdhsa_user_sgpr_queue_ptr 0
		.amdhsa_user_sgpr_kernarg_segment_ptr 1
		.amdhsa_user_sgpr_dispatch_id 0
		.amdhsa_user_sgpr_kernarg_preload_length 0
		.amdhsa_user_sgpr_kernarg_preload_offset 0
		.amdhsa_user_sgpr_private_segment_size 0
		.amdhsa_uses_dynamic_stack 0
		.amdhsa_enable_private_segment 0
		.amdhsa_system_sgpr_workgroup_id_x 1
		.amdhsa_system_sgpr_workgroup_id_y 0
		.amdhsa_system_sgpr_workgroup_id_z 0
		.amdhsa_system_sgpr_workgroup_info 0
		.amdhsa_system_vgpr_workitem_id 2
		.amdhsa_next_free_vgpr 247
		.amdhsa_next_free_sgpr 102
		.amdhsa_accum_offset 248
		.amdhsa_reserve_vcc 1
		.amdhsa_float_round_mode_32 0
		.amdhsa_float_round_mode_16_64 0
		.amdhsa_float_denorm_mode_32 3
		.amdhsa_float_denorm_mode_16_64 3
		.amdhsa_dx10_clamp 1
		.amdhsa_ieee_mode 1
		.amdhsa_fp16_overflow 0
		.amdhsa_tg_split 0
		.amdhsa_exception_fp_ieee_invalid_op 0
		.amdhsa_exception_fp_denorm_src 0
		.amdhsa_exception_fp_ieee_div_zero 0
		.amdhsa_exception_fp_ieee_overflow 0
		.amdhsa_exception_fp_ieee_underflow 0
		.amdhsa_exception_fp_ieee_inexact 0
		.amdhsa_exception_int_div_zero 0
	.end_amdhsa_kernel

; __global__ void __launch_bounds__(NTHR) fwd_megakernel(const Params P) {
amdhsa.kernels:
  - .agpr_count:     0
    .args:
      - .offset:         0
        .size:           432
        .value_kind:     by_value
      - .offset:         432
        .size:           4
        .value_kind:     hidden_block_count_x
      - .offset:         436
        .size:           4
        .value_kind:     hidden_block_count_y
      - .offset:         440
        .size:           4
        .value_kind:     hidden_block_count_z
      - .offset:         444
        .size:           2
        .value_kind:     hidden_group_size_x
      - .offset:         446
        .size:           2
        .value_kind:     hidden_group_size_y
      - .offset:         448
        .size:           2
        .value_kind:     hidden_group_size_z
      - .offset:         450
        .size:           2
        .value_kind:     hidden_remainder_x
      - .offset:         452
        .size:           2
        .value_kind:     hidden_remainder_y
      - .offset:         454
        .size:           2
        .value_kind:     hidden_remainder_z
      - .offset:         472
        .size:           8
        .value_kind:     hidden_global_offset_x
      - .offset:         480
        .size:           8
        .value_kind:     hidden_global_offset_y
      - .offset:         488
        .size:           8
        .value_kind:     hidden_global_offset_z
      - .offset:         496
        .size:           2
        .value_kind:     hidden_grid_dims
      - .offset:         520
        .size:           8
        .value_kind:     hidden_multigrid_sync_arg
      - .offset:         552
        .size:           4
        .value_kind:     hidden_dynamic_lds_size
    .group_segment_fixed_size: 32
    .kernarg_segment_align: 8
    .kernarg_segment_size: 688
    .language:       OpenCL C
    .language_version:
      - 2
      - 0
    .max_flat_workgroup_size: 512
    .name:           _Z14fwd_megakernel6Params
    .private_segment_fixed_size: 0
    .sgpr_count:     108
    .sgpr_spill_count: 284
    .symbol:         _Z14fwd_megakernel6Params.kd
    .uniform_work_group_size: 1
    .uses_dynamic_stack: false
    .vgpr_count:     247
    .vgpr_spill_count: 0
    .wavefront_size: 64
